# sample-attention front v4: P.V folded into the key-norm block as filler, one merged cross-lane reduction and one norm-table write for both key blocks, lane addresses hoisted out of the tile loop
# speedup vs baseline: 1.0170x; 1.0081x over previous
; DI void attn_sample_phase(const Args& a, LAS unsigned char* lds, int vcu, int G, int tid, int lane, int wave) {
;     ...
;         for (int s9 = 0; s9 < 9; ++s9) qfr[s9] = *(const bf16x8*)(QS + ((size_t)bd * 32 + (wave & 1) * 16 + r16) * CSW + 32 * s9 + 8 * q4);
;         f32x2 rcur = *(const f32x2*)(rc + (split * 4096 + krow) * 16 + 2 * kp), rsur = *(const f32x2*)(rs + (split * 4096 + krow) * 16 + 2 * kp);
;         __syncthreads();
;         SA_LOAD(0, a0, a1, a2, a3, aka, akb);
;         SA_CONVERT(0, 0, a0, a1, a2, a3, aka, akb);
;         SA_LOAD(1, a0, a1, a2, a3, aka, akb);
;         __syncthreads();
;         f32x16 accT = {}; float lsum = 0.f; int c3 = 0;
; #pragma unroll 1
;         for (int j = 0; j < 128; ++j) {
.LBB0_900:
	s_or_b64 exec, exec, s[18:19]
	v_mov_b32_e32 v4, v3
	v_mov_b32_e32 v5, v3
	v_mov_b32_e32 v6, v3
	v_mov_b32_e32 v7, v3
	v_mov_b32_e32 v8, v3
	v_mov_b32_e32 v9, v3
	v_mov_b32_e32 v10, v3
	v_mov_b32_e32 v11, v3
	v_mov_b32_e32 v12, v3
	v_mov_b32_e32 v13, v3
	v_mov_b32_e32 v14, v3
	v_mov_b32_e32 v15, v3
	v_mov_b32_e32 v16, v3
	v_mov_b32_e32 v17, v3
	v_mov_b32_e32 v2, v3
	v_mov_b64_e32 v[18:19], v[16:17]
	s_mov_b32 s17, 0
	v_mov_b32_e32 v211, 0
	s_mov_b32 s24, 64
	s_mov_b32 s25, 2
	v_mov_b64_e32 v[16:17], v[14:15]
	v_mov_b64_e32 v[14:15], v[12:13]
	v_mov_b64_e32 v[12:13], v[10:11]
	v_mov_b64_e32 v[10:11], v[8:9]
	v_mov_b64_e32 v[8:9], v[6:7]
	v_mov_b64_e32 v[6:7], v[4:5]
	v_mov_b64_e32 v[4:5], v[2:3]
	v_readfirstlane_b32 s99, v158
	v_lshrrev_b32_e32 v255, 5, v142
	v_lshlrev_b32_e32 v255, 6, v255
	v_lshl_add_u32 v255, v140, 2, v255
	s_lshl_b32 s99, s99, 7
	v_lshl_add_u32 v255, v158, 7, v255
	v_add_u32_e32 v255, 0x17600, v255
	s_waitcnt lgkmcnt(0)
	s_barrier
	s_branch .LBB0_902

; #define LAS __attribute__((address_space(3)))
; DI void attn_sample_phase(const Args& a, LAS unsigned char* lds, int vcu, int G, int tid, int lane, int wave) {
;     ...
;             { const LAS unsigned char* c8b = C8 + (j & 1) * 8704; const LAS float* spe = SSPE + (j & 1) * 32;
; #pragma unroll
;                 for (int kb = 0; kb < 2; ++kb) { f32x4 acc[4] = {};
; #pragma unroll
;                     for (int ks = 0; ks < 2; ++ks) { const LAS unsigned char* ap = c8b + (kb * 16 + r16) * 272 + 128 * ks + 32 * q4;
;                         const u32x4 x0 = *(const LAS u32x4*)ap, x1 = *(const LAS u32x4*)(ap + 16);
;                         const v8i_t af = {(int)x0.x, (int)x0.y, (int)x0.z, (int)x0.w, (int)x1.x, (int)x1.y, (int)x1.z, (int)x1.w};
; #pragma unroll
;                         for (int nb = 0; nb < 4; ++nb) acc[nb] = __builtin_amdgcn_mfma_scale_f32_16x16x128_f8f6f4(af, wf8[nb][ks], acc[nb], 0, 0, 0, 0x7F7F7F7F, 0, 0x7F7F7F7F); }
;                     f32x4 sq = (acc[0] * acc[0] + acc[1] * acc[1] + acc[2] * acc[2] + acc[3] * acc[3]) * (1.f / 256.f);
;                     sq.x = row16_sum(sq.x); sq.y = row16_sum(sq.y); sq.z = row16_sum(sq.z); sq.w = row16_sum(sq.w);
;                     if (r16 == 0) { const f32x4 pe = *(const LAS f32x4*)(spe + kb * 16 + 4 * q4); f32x4 r;
;                         r.x = __builtin_amdgcn_rsqf((sq.x + pe.x) * (1.f / 96.f) + EPS); r.y = __builtin_amdgcn_rsqf((sq.y + pe.y) * (1.f / 96.f) + EPS);
;                         r.z = __builtin_amdgcn_rsqf((sq.z + pe.z) * (1.f / 96.f) + EPS); r.w = __builtin_amdgcn_rsqf((sq.w + pe.w) * (1.f / 96.f) + EPS);
;                         *(LAS f32x4*)(RI + wave * 32 + kb * 16 + 4 * q4) = r; } } }
.Lsa_front:
.LBB0_904:
	s_and_b32 s8, s26, 1
	s_mul_i32 s9, s8, 0x2200
	v_add_u32_e32 v2, s9, v202
	s_lshl_b32 s8, s8, 7
	s_add_i32 s8, s8, 0x400
	s_sub_i32 s8, s8, s99
	v_add_u32_e32 v254, s8, v255
	ds_read_b128 v[212:215], v2 offset:56832
	ds_read_b128 v[216:219], v2 offset:56848
	ds_read_b128 v[236:239], v2 offset:56960
	ds_read_b128 v[240:243], v2 offset:56976
	ds_read_b128 v[246:249], v2 offset:61184
	ds_read_b128 v[250:253], v2 offset:61200
	ds_read_b32 v232, v254
	s_waitcnt lgkmcnt(5)
	v_mfma_f32_16x16x128_f8f6f4 v[220:223], v[36:43], v[212:219], 0
	v_mfma_f32_16x16x128_f8f6f4 v[136:139], v[20:27], v[212:219], 0
	v_mfma_f32_16x16x128_f8f6f4 v[224:227], v[52:59], v[212:219], 0
	v_mfma_f32_16x16x128_f8f6f4 v[228:231], v[68:75], v[212:219], 0
	s_waitcnt lgkmcnt(3)
	v_mfma_f32_16x16x128_f8f6f4 v[220:223], v[44:51], v[236:243], v[220:223]
	ds_read_b128 v[212:215], v2 offset:61312
	ds_read_b128 v[216:219], v2 offset:61328
	v_mfma_f32_16x16x128_f8f6f4 v[136:139], v[28:35], v[236:243], v[136:139]
	v_mfma_f32_16x16x128_f8f6f4 v[224:227], v[60:67], v[236:243], v[224:227]
	v_mfma_f32_16x16x128_f8f6f4 v[228:231], v[76:83], v[236:243], v[228:231]
	s_mul_i32 s9, s98, 0x2500
	s_addk_i32 s9, 0xdb00
	s_cmp_lg_u32 s98, 0
	s_cselect_b32 s9, s9, 0x4a00
	v_lshl_add_u32 v2, s9, 1, v201
	s_nop 1
	v_mul_f32_e32 v234, v220, v220
	v_fmac_f32_e32 v234, v221, v221
	v_fmac_f32_e32 v234, v222, v222
	v_fmac_f32_e32 v234, v223, v223
	s_waitcnt lgkmcnt(3)
	v_mfma_f32_16x16x128_f8f6f4 v[220:223], v[36:43], v[246:253], 0
	v_fmac_f32_e32 v234, v136, v136
	v_fmac_f32_e32 v234, v137, v137
	v_fmac_f32_e32 v234, v138, v138
	v_fmac_f32_e32 v234, v139, v139
	v_mfma_f32_16x16x128_f8f6f4 v[136:139], v[68:75], v[246:253], 0
	v_fmac_f32_e32 v234, v224, v224
	v_fmac_f32_e32 v234, v225, v225
	v_fmac_f32_e32 v234, v226, v226
	v_fmac_f32_e32 v234, v227, v227
	v_mfma_f32_16x16x128_f8f6f4 v[224:227], v[20:27], v[246:253], 0
	v_fmac_f32_e32 v234, v228, v228
	v_fmac_f32_e32 v234, v229, v229
	v_fmac_f32_e32 v234, v230, v230
	v_fmac_f32_e32 v234, v231, v231
	v_mfma_f32_16x16x128_f8f6f4 v[228:231], v[52:59], v[246:253], 0
	s_waitcnt lgkmcnt(0)
	v_mfma_f32_16x16x128_f8f6f4 v[220:223], v[44:51], v[212:219], v[220:223]
	s_cmp_eq_u32 s25, 2
	s_cbranch_scc1 .Lsa_nopvA
	ds_read_b64_tr_b16 v[236:237], v2
	ds_read_b64_tr_b16 v[238:239], v2 offset:2368
	ds_read_b128 v[246:249], v196
	ds_read_b128 v[250:253], v196 offset:32
	ds_read_b64_tr_b16 v[240:241], v2 offset:9472
	ds_read_b64_tr_b16 v[242:243], v2 offset:11840
.Lsa_nopvA:
	v_mfma_f32_16x16x128_f8f6f4 v[136:139], v[76:83], v[212:219], v[136:139]
	v_mfma_f32_16x16x128_f8f6f4 v[224:227], v[28:35], v[212:219], v[224:227]
	v_mfma_f32_16x16x128_f8f6f4 v[228:231], v[60:67], v[212:219], v[228:231]
	s_cbranch_scc1 .Lsa_nopvB
	s_waitcnt lgkmcnt(3)
	v_mfma_f32_32x32x16_bf16 v[4:19], v[236:239], v[246:249], v[4:19]
	s_waitcnt lgkmcnt(0)
	v_mfma_f32_32x32x16_bf16 v[4:19], v[240:243], v[250:253], v[4:19]
	s_branch .Lsa_pvdone
.Lsa_nopvB:
	s_nop 7
.Lsa_pvdone:
	v_mul_f32_e32 v235, v220, v220
	v_fmac_f32_e32 v235, v221, v221
	v_fmac_f32_e32 v235, v222, v222
	v_fmac_f32_e32 v235, v223, v223
	v_fmac_f32_e32 v235, v136, v136
	v_fmac_f32_e32 v235, v137, v137
	v_fmac_f32_e32 v235, v138, v138
	v_fmac_f32_e32 v235, v139, v139
	v_fmac_f32_e32 v235, v224, v224
	v_fmac_f32_e32 v235, v225, v225
	v_fmac_f32_e32 v235, v226, v226
	v_fmac_f32_e32 v235, v227, v227
	v_fmac_f32_e32 v235, v228, v228
	v_fmac_f32_e32 v235, v229, v229
	v_fmac_f32_e32 v235, v230, v230
	v_fmac_f32_e32 v235, v231, v231
	s_nop 1
	v_permlane32_swap_b32_e32 v234, v235
	v_add_f32_e32 v234, v234, v235
	v_mov_b32_e32 v233, v234
	s_nop 1
	v_permlane16_swap_b32_e32 v233, v234
	v_add_f32_e32 v234, v234, v233
	v_fmamk_f32 v234, v234, 0x3b800000, v232
	v_fmamk_f32 v234, v234, 0x3c2aaaab, v209
	v_rsq_f32_e32 v234, v234
	ds_write_b32 v255, v234
